# perm4+wb1 + P0 RMSNorm rows handed out from per-XCD work counters after the first static group (dynamic balance of the bandwidth-bound pass)
# speedup vs baseline: 1.0040x; 1.0009x over previous
.LBB0_74:
	v_writelane_b32 v245, s36, 19
	s_nop 1
	v_writelane_b32 v245, s37, 20
	s_or_b64 exec, exec, s[0:1]
	v_readlane_b32 s40, v245, 0
	v_lshlrev_b32_e32 v96, 5, v97
	v_readlane_b32 s41, v245, 1
	s_nop 4
	global_load_dwordx4 v[16:19], v96, s[40:41] offset:16
	global_load_dwordx4 v[20:23], v96, s[40:41]
	global_load_dwordx4 v[0:3], v96, s[66:67] offset:16
	global_load_dwordx4 v[4:7], v96, s[66:67]
	global_load_dwordx4 v[24:27], v96, s[40:41] offset:2064
	global_load_dwordx4 v[28:31], v96, s[40:41] offset:2048
	global_load_dwordx4 v[8:11], v96, s[66:67] offset:2064
	global_load_dwordx4 v[12:15], v96, s[66:67] offset:2048
	s_mul_i32 s34, s96, 24
	s_add_i32 s0, s29, s34
	v_mov_b32_e32 v33, 0
	s_cmp_lt_i32 s0, 0x8200
	v_mbcnt_lo_u32_b32 v221, -1, 0
	s_mov_b32 s16, s29
	v_readlane_b32 s42, v245, 2
	v_readlane_b32 s43, v245, 3
	v_readlane_b32 s44, v245, 4
	v_readlane_b32 s45, v245, 5
	v_readlane_b32 s46, v245, 6
	v_readlane_b32 s47, v245, 7
	v_readlane_b32 s48, v245, 8
	v_readlane_b32 s49, v245, 9
	v_readlane_b32 s50, v245, 10
	v_readlane_b32 s51, v245, 11
	v_readlane_b32 s52, v245, 12
	v_readlane_b32 s53, v245, 13
	v_readlane_b32 s54, v245, 14
	v_readlane_b32 s55, v245, 15
	s_mov_b64 s[36:37], s[40:41]
	s_cbranch_scc0 .LBB0_77
	v_mbcnt_hi_u32_b32 v32, -1, v221
	v_and_b32_e32 v34, 64, v32
	v_add_u32_e32 v34, 64, v34
	v_xor_b32_e32 v35, 1, v32
	v_cmp_lt_i32_e32 vcc, v35, v34
	s_mov_b64 s[0:1], 0x3600000
	s_lshl_b32 s11, s96, 4
	v_cndmask_b32_e32 v35, v32, v35, vcc
	v_lshlrev_b32_e32 v107, 2, v35
	v_xor_b32_e32 v35, 2, v32
	v_cmp_lt_i32_e32 vcc, v35, v34
	s_mov_b32 s10, 0x3a800000
	s_mov_b32 s12, 0x358637bd
	v_cndmask_b32_e32 v35, v32, v35, vcc
	v_lshlrev_b32_e32 v108, 2, v35
	v_xor_b32_e32 v35, 4, v32
	v_cmp_lt_i32_e32 vcc, v35, v34
	s_mov_b32 s13, 0x800000
	s_mov_b32 s16, s29
	v_cndmask_b32_e32 v35, v32, v35, vcc
	v_lshlrev_b32_e32 v109, 2, v35
	v_xor_b32_e32 v35, 8, v32
	v_cmp_lt_i32_e32 vcc, v35, v34
	s_nop 1
	v_cndmask_b32_e32 v35, v32, v35, vcc
	v_lshlrev_b32_e32 v110, 2, v35
	v_xor_b32_e32 v35, 16, v32
	v_cmp_lt_i32_e32 vcc, v35, v34
	s_nop 1
	v_cndmask_b32_e32 v35, v32, v35, vcc
	v_lshlrev_b32_e32 v111, 2, v35
	v_xor_b32_e32 v35, 32, v32
	v_cmp_lt_i32_e32 vcc, v35, v34
	s_nop 1
	v_cndmask_b32_e32 v32, v32, v35, vcc
	v_lshlrev_b32_e32 v112, 2, v32
	v_lshlrev_b32_e32 v32, 1, v106
	v_lshl_add_u64 v[32:33], s[20:21], 0, v[32:33]
	v_lshl_add_u64 v[98:99], v[32:33], 0, s[0:1]
	s_waitcnt vmcnt(0)
	s_and_b32 s98, s2, 7
	s_lshl_b32 s98, s98, 6
	s_add_i32 s98, s98, 0x8200
	v_mov_b32_e32 v141, s98
	v_mov_b32_e32 v142, 1
	v_mov_b32_e32 v140, 0x7fffffff
.LBB0_76:
	s_mov_b64 s[100:101], exec
	s_mov_b64 exec, 1
	global_atomic_add v140, v141, v142, s[62:63] sc0
	s_mov_b64 exec, s[100:101]
	s_add_i32 s0, s34, s16
	s_add_i32 s1, s16, 0xffff8000
	s_ashr_i32 s17, s16, 31
	s_cmp_lt_i32 s16, 0x8000
	s_cselect_b32 s19, s17, 0
	s_cselect_b32 s18, s16, s1
	s_cselect_b32 s1, s5, s7
	s_cselect_b32 s22, s4, s6
	s_lshl_b64 s[18:19], s[18:19], 12
	s_add_u32 s18, s22, s18
	s_addc_u32 s19, s1, s19
	s_add_i32 s24, s16, s92
	v_lshlrev_b32_e32 v80, 2, v106
	s_add_i32 s1, s24, 0xffff8000
	s_ashr_i32 s25, s24, 31
	global_load_dwordx4 v[60:63], v80, s[18:19] nt
	global_load_dwordx4 v[52:55], v80, s[18:19] offset:16 nt
	global_load_dwordx4 v[48:51], v80, s[18:19] offset:2064 nt
	global_load_dwordx4 v[56:59], v80, s[18:19] offset:2048 nt
	s_cmp_lt_i32 s24, 0x8000
	s_cselect_b32 s19, s25, 0
	s_cselect_b32 s18, s24, s1
	s_cselect_b32 s1, s5, s7
	s_cselect_b32 s22, s4, s6
	s_lshl_b64 s[18:19], s[18:19], 12
	s_add_u32 s18, s22, s18
	s_addc_u32 s19, s1, s19
	s_add_i32 s26, s11, s16
	s_add_i32 s31, s24, s92
	s_add_i32 s1, s26, 0xffff8000
	s_ashr_i32 s27, s26, 31
	global_load_dwordx4 v[76:79], v80, s[18:19] nt
	global_load_dwordx4 v[68:71], v80, s[18:19] offset:16 nt
	global_load_dwordx4 v[64:67], v80, s[18:19] offset:2064 nt
	global_load_dwordx4 v[72:75], v80, s[18:19] offset:2048 nt
	s_cmp_lt_i32 s26, 0x8000
	s_cselect_b32 s19, s27, 0
	s_cselect_b32 s18, s26, s1
	s_cselect_b32 s1, s5, s7
	s_cselect_b32 s22, s4, s6
	s_lshl_b64 s[18:19], s[18:19], 12
	s_add_u32 s18, s22, s18
	s_addc_u32 s19, s1, s19
	s_add_i32 s22, s0, 0xffff8000
	s_ashr_i32 s1, s0, 31
	global_load_dwordx4 v[36:39], v80, s[18:19] offset:16 nt
	global_load_dwordx4 v[44:47], v80, s[18:19] nt
	global_load_dwordx4 v[40:43], v80, s[18:19] offset:2048 nt
	global_load_dwordx4 v[32:35], v80, s[18:19] offset:2064 nt
	s_cmp_lt_i32 s0, 0x8000
	s_cselect_b32 s19, s1, 0
	s_cselect_b32 s18, s0, s22
	s_cselect_b32 s22, s5, s7
	s_cselect_b32 s23, s4, s6
	s_lshl_b64 s[18:19], s[18:19], 12
	s_add_u32 s18, s23, s18
	s_addc_u32 s19, s22, s19
	global_load_dwordx4 v[84:87], v80, s[18:19] offset:16 nt
	global_load_dwordx4 v[92:95], v80, s[18:19] nt
	global_load_dwordx4 v[88:91], v80, s[18:19] offset:2048 nt
	s_nop 0
	global_load_dwordx4 v[80:83], v80, s[18:19] offset:2064 nt
	v_mov_b64_e32 v[100:101], s[12:13]
	s_lshl_b64 s[22:23], s[16:17], 11
	s_lshl_b64 s[0:1], s[0:1], 11
	s_add_i32 s16, s31, s11
	s_lshl_b64 s[24:25], s[24:25], 11
	s_lshl_b64 s[26:27], s[26:27], 11
	v_lshl_add_u64 v[102:103], v[98:99], 0, s[0:1]
	s_add_i32 s0, s34, s16
	s_cmp_gt_i32 s0, 0x81ff
	v_lshl_add_u64 v[114:115], v[98:99], 0, s[22:23]
	v_lshl_add_u64 v[116:117], v[98:99], 0, s[24:25]
	v_lshl_add_u64 v[104:105], v[98:99], 0, s[26:27]
	s_waitcnt vmcnt(15)
	v_pk_mul_f32 v[118:119], v[62:63], v[62:63]
	v_pk_mul_f32 v[120:121], v[60:61], v[60:61]
	s_waitcnt vmcnt(14)
	v_pk_mul_f32 v[122:123], v[54:55], v[54:55]
	v_pk_mul_f32 v[124:125], v[52:53], v[52:53]
	v_pk_mov_b32 v[130:131], v[120:121], v[118:119] op_sel:[1,0]
	v_mov_b32_e32 v121, v119
	v_pk_mov_b32 v[118:119], v[124:125], v[122:123] op_sel:[1,0]
	v_mov_b32_e32 v125, v123
	s_waitcnt vmcnt(13)
	v_mul_f32_e32 v129, v49, v49
	s_waitcnt vmcnt(12)
	v_mul_f32_e32 v126, v57, v57
	v_mul_f32_e32 v128, v59, v59
	v_pk_add_f32 v[120:121], v[130:131], v[120:121]
	v_pk_add_f32 v[118:119], v[118:119], v[124:125]
	v_mul_f32_e32 v113, v48, v48
	v_mul_f32_e32 v132, v50, v50
	v_mul_f32_e32 v133, v51, v51
	v_pk_fma_f32 v[122:123], v[56:57], v[56:57], v[126:127] op_sel_hi:[1,1,0]
	v_pk_fma_f32 v[126:127], v[58:59], v[58:59], v[128:129] op_sel_hi:[1,1,0]
	v_pk_add_f32 v[120:121], v[120:121], v[120:121] op_sel:[0,1] op_sel_hi:[1,0]
	v_pk_add_f32 v[118:119], v[118:119], v[118:119] op_sel:[0,1] op_sel_hi:[1,0]
	v_mov_b32_e32 v123, v132
	v_mov_b32_e32 v127, v133
	v_mov_b32_e32 v121, v113
	v_mov_b32_e32 v119, v129
	v_pk_add_f32 v[122:123], v[122:123], v[126:127]
	v_pk_add_f32 v[118:119], v[120:121], v[118:119]
	s_waitcnt vmcnt(11)
	v_pk_mul_f32 v[120:121], v[78:79], v[78:79]
	v_pk_add_f32 v[118:119], v[118:119], v[122:123]
	v_pk_mul_f32 v[122:123], v[76:77], v[76:77]
	s_waitcnt vmcnt(10)
	v_pk_mul_f32 v[124:125], v[70:71], v[70:71]
	v_pk_mul_f32 v[126:127], v[68:69], v[68:69]
	v_pk_mov_b32 v[132:133], v[122:123], v[120:121] op_sel:[1,0]
	v_mov_b32_e32 v123, v121
	v_pk_mov_b32 v[120:121], v[126:127], v[124:125] op_sel:[1,0]
	v_mov_b32_e32 v127, v125
	s_waitcnt vmcnt(8)
	v_mul_f32_e32 v128, v73, v73
	v_mul_f32_e32 v130, v75, v75
	v_pk_add_f32 v[122:123], v[132:133], v[122:123]
	v_pk_add_f32 v[120:121], v[120:121], v[126:127]
	v_mul_f32_e32 v113, v64, v64
	v_mul_f32_e32 v134, v65, v65
	v_mul_f32_e32 v135, v66, v66
	v_mul_f32_e32 v136, v67, v67
	v_pk_fma_f32 v[124:125], v[72:73], v[72:73], v[128:129] op_sel_hi:[1,1,0]
	v_pk_fma_f32 v[128:129], v[74:75], v[74:75], v[130:131] op_sel_hi:[1,1,0]
	v_pk_add_f32 v[122:123], v[122:123], v[122:123] op_sel:[0,1] op_sel_hi:[1,0]
	v_pk_add_f32 v[120:121], v[120:121], v[120:121] op_sel:[0,1] op_sel_hi:[1,0]
	v_mov_b32_e32 v125, v135
	v_mov_b32_e32 v129, v136
	v_mov_b32_e32 v123, v113
	v_mov_b32_e32 v121, v134
	v_pk_add_f32 v[124:125], v[124:125], v[128:129]
	v_pk_add_f32 v[120:121], v[122:123], v[120:121]
	v_mov_b32_e32 v131, v118
	v_pk_add_f32 v[120:121], v[120:121], v[124:125]
	s_waitcnt vmcnt(6)
	v_pk_mul_f32 v[122:123], v[46:47], v[46:47]
	v_pk_mul_f32 v[124:125], v[44:45], v[44:45]
	v_pk_mul_f32 v[126:127], v[38:39], v[38:39]
	v_pk_mul_f32 v[128:129], v[36:37], v[36:37]
	s_waitcnt vmcnt(5)
	v_mul_f32_e32 v118, v41, v41
	v_mul_f32_e32 v130, v43, v43
	s_waitcnt vmcnt(4)
	v_mul_f32_e32 v137, v34, v34
	v_mul_f32_e32 v138, v35, v35
	v_pk_mov_b32 v[132:133], v[124:125], v[122:123] op_sel:[1,0]
	v_mov_b32_e32 v125, v123
	v_pk_mov_b32 v[122:123], v[128:129], v[126:127] op_sel:[1,0]
	v_mov_b32_e32 v129, v127
	v_pk_fma_f32 v[126:127], v[40:41], v[40:41], v[118:119] op_sel_hi:[1,1,0]
	v_pk_fma_f32 v[134:135], v[42:43], v[42:43], v[130:131] op_sel_hi:[1,1,0]
	v_mov_b32_e32 v130, v120
	v_mov_b32_e32 v118, v121
	v_pk_add_f32 v[120:121], v[132:133], v[124:125]
	v_pk_add_f32 v[122:123], v[122:123], v[128:129]
	v_mov_b32_e32 v127, v137
	v_mov_b32_e32 v135, v138
	v_pk_add_f32 v[118:119], v[130:131], v[118:119]
	v_mul_f32_e32 v113, v32, v32
	v_mul_f32_e32 v136, v33, v33
	v_pk_add_f32 v[120:121], v[120:121], v[120:121] op_sel:[0,1] op_sel_hi:[1,0]
	v_pk_add_f32 v[122:123], v[122:123], v[122:123] op_sel:[0,1] op_sel_hi:[1,0]
	v_pk_add_f32 v[124:125], v[126:127], v[134:135]
	ds_bpermute_b32 v127, v107, v119
	ds_bpermute_b32 v126, v107, v118
	v_mov_b32_e32 v121, v113
	v_mov_b32_e32 v123, v136
	v_pk_add_f32 v[120:121], v[120:121], v[122:123]
	s_waitcnt vmcnt(2)
	v_pk_mul_f32 v[122:123], v[94:95], v[94:95]
	v_pk_mul_f32 v[128:129], v[92:93], v[92:93]
	v_pk_mul_f32 v[130:131], v[86:87], v[86:87]
	v_pk_mul_f32 v[132:133], v[84:85], v[84:85]
	v_pk_add_f32 v[120:121], v[120:121], v[124:125]
	v_pk_mov_b32 v[124:125], v[128:129], v[122:123] op_sel:[1,0]
	v_mov_b32_e32 v129, v123
	v_pk_mov_b32 v[122:123], v[132:133], v[130:131] op_sel:[1,0]
	v_mov_b32_e32 v133, v131
	s_waitcnt vmcnt(0)
	v_mul_f32_e32 v137, v81, v81
	v_mul_f32_e32 v134, v89, v89
	v_mul_f32_e32 v136, v91, v91
	v_pk_add_f32 v[124:125], v[124:125], v[128:129]
	v_pk_add_f32 v[122:123], v[122:123], v[132:133]
	v_mul_f32_e32 v113, v80, v80
	v_mul_f32_e32 v138, v82, v82
	v_mul_f32_e32 v139, v83, v83
	v_pk_fma_f32 v[130:131], v[88:89], v[88:89], v[134:135] op_sel_hi:[1,1,0]
	v_pk_fma_f32 v[134:135], v[90:91], v[90:91], v[136:137] op_sel_hi:[1,1,0]
	v_pk_add_f32 v[124:125], v[124:125], v[124:125] op_sel:[0,1] op_sel_hi:[1,0]
	v_pk_add_f32 v[122:123], v[122:123], v[122:123] op_sel:[0,1] op_sel_hi:[1,0]
	s_waitcnt lgkmcnt(0)
	v_pk_add_f32 v[118:119], v[118:119], v[126:127]
	v_mov_b32_e32 v131, v138
	v_mov_b32_e32 v135, v139
	v_mov_b32_e32 v125, v113
	v_mov_b32_e32 v123, v137
	ds_bpermute_b32 v127, v108, v119
	ds_bpermute_b32 v126, v108, v118
	v_pk_add_f32 v[130:131], v[130:131], v[134:135]
	v_pk_add_f32 v[122:123], v[124:125], v[122:123]
	v_mov_b32_e32 v129, v120
	v_pk_add_f32 v[122:123], v[122:123], v[130:131]
	s_waitcnt lgkmcnt(0)
	v_pk_add_f32 v[118:119], v[118:119], v[126:127]
	v_mov_b32_e32 v128, v122
	v_mov_b32_e32 v120, v123
	v_pk_add_f32 v[120:121], v[128:129], v[120:121]
	ds_bpermute_b32 v123, v107, v121
	ds_bpermute_b32 v122, v107, v120
	ds_bpermute_b32 v125, v109, v119
	ds_bpermute_b32 v124, v109, v118
	s_waitcnt lgkmcnt(2)
	v_pk_add_f32 v[120:121], v[120:121], v[122:123]
	ds_bpermute_b32 v123, v108, v121
	s_waitcnt lgkmcnt(1)
	v_pk_add_f32 v[118:119], v[118:119], v[124:125]
	ds_bpermute_b32 v122, v108, v120
	ds_bpermute_b32 v125, v110, v119
	ds_bpermute_b32 v124, v110, v118
	s_waitcnt lgkmcnt(2)
	v_pk_add_f32 v[120:121], v[120:121], v[122:123]
	ds_bpermute_b32 v123, v109, v121
	s_waitcnt lgkmcnt(1)
	v_pk_add_f32 v[118:119], v[118:119], v[124:125]
	ds_bpermute_b32 v122, v109, v120
	ds_bpermute_b32 v125, v111, v119
	ds_bpermute_b32 v124, v111, v118
	s_waitcnt lgkmcnt(2)
	v_pk_add_f32 v[120:121], v[120:121], v[122:123]
	ds_bpermute_b32 v123, v110, v121
	s_waitcnt lgkmcnt(1)
	v_pk_add_f32 v[118:119], v[118:119], v[124:125]
	ds_bpermute_b32 v122, v110, v120
	ds_bpermute_b32 v125, v112, v119
	ds_bpermute_b32 v124, v112, v118
	s_waitcnt lgkmcnt(2)
	v_pk_add_f32 v[120:121], v[120:121], v[122:123]
	ds_bpermute_b32 v123, v111, v121
	s_waitcnt lgkmcnt(1)
	v_pk_add_f32 v[118:119], v[118:119], v[124:125]
	ds_bpermute_b32 v122, v111, v120
	v_pk_fma_f32 v[118:119], v[118:119], s[10:11], v[100:101] op_sel_hi:[1,0,0]
	s_nop 0
	v_mul_f32_e32 v113, 0x4b800000, v119
	v_mul_f32_e32 v124, 0x4b800000, v118
	v_cmp_gt_f32_e32 vcc, s13, v118
	v_cmp_gt_f32_e64 s[0:1], s13, v119
	s_nop 0
	v_cndmask_b32_e32 v118, v118, v124, vcc
	v_cndmask_b32_e64 v113, v119, v113, s[0:1]
	v_rsq_f32_e32 v113, v113
	v_rsq_f32_e32 v124, v118
	s_waitcnt lgkmcnt(0)
	v_pk_add_f32 v[118:119], v[120:121], v[122:123]
	ds_bpermute_b32 v121, v112, v119
	ds_bpermute_b32 v120, v112, v118
	v_mul_f32_e32 v122, 0x45800000, v113
	v_mul_f32_e32 v123, 0x45800000, v124
	v_cndmask_b32_e64 v122, v113, v122, s[0:1]
	v_cndmask_b32_e32 v124, v124, v123, vcc
	v_pk_mul_f32 v[60:61], v[60:61], v[122:123] op_sel_hi:[1,0]
	v_pk_mul_f32 v[62:63], v[62:63], v[122:123] op_sel_hi:[1,0]
	v_pk_mul_f32 v[52:53], v[52:53], v[122:123] op_sel_hi:[1,0]
	v_pk_mul_f32 v[54:55], v[54:55], v[122:123] op_sel_hi:[1,0]
	v_pk_mul_f32 v[64:65], v[64:65], v[124:125] op_sel_hi:[1,0]
	v_pk_mul_f32 v[56:57], v[56:57], v[122:123] op_sel_hi:[1,0]
	v_pk_mul_f32 v[58:59], v[58:59], v[122:123] op_sel_hi:[1,0]
	v_pk_mul_f32 v[48:49], v[48:49], v[122:123] op_sel_hi:[1,0]
	v_pk_mul_f32 v[50:51], v[50:51], v[122:123] op_sel_hi:[1,0]
	v_pk_mul_f32 v[76:77], v[76:77], v[124:125] op_sel_hi:[1,0]
	v_pk_mul_f32 v[78:79], v[78:79], v[124:125] op_sel_hi:[1,0]
	v_pk_mul_f32 v[68:69], v[68:69], v[124:125] op_sel_hi:[1,0]
	v_pk_mul_f32 v[70:71], v[70:71], v[124:125] op_sel_hi:[1,0]
	v_pk_mul_f32 v[72:73], v[72:73], v[124:125] op_sel_hi:[1,0]
	v_pk_mul_f32 v[74:75], v[74:75], v[124:125] op_sel_hi:[1,0]
	v_pk_mul_f32 v[66:67], v[66:67], v[124:125] op_sel_hi:[1,0]
	v_pk_mul_f32 v[62:63], v[22:23], v[62:63]
	v_pk_mul_f32 v[60:61], v[20:21], v[60:61]
	v_pk_mul_f32 v[54:55], v[18:19], v[54:55]
	v_pk_mul_f32 v[52:53], v[16:17], v[52:53]
	v_pk_mul_f32 v[64:65], v[24:25], v[64:65]
	s_waitcnt lgkmcnt(0)
	v_pk_add_f32 v[118:119], v[118:119], v[120:121]
	v_pk_mul_f32 v[58:59], v[30:31], v[58:59]
	v_pk_mul_f32 v[56:57], v[28:29], v[56:57]
	v_pk_mul_f32 v[122:123], v[26:27], v[50:51]
	v_pk_mul_f32 v[124:125], v[24:25], v[48:49]
	v_pk_mul_f32 v[78:79], v[22:23], v[78:79]
	v_pk_mul_f32 v[76:77], v[20:21], v[76:77]
	v_pk_mul_f32 v[70:71], v[18:19], v[70:71]
	v_pk_mul_f32 v[68:69], v[16:17], v[68:69]
	v_pk_mul_f32 v[74:75], v[30:31], v[74:75]
	v_pk_mul_f32 v[72:73], v[28:29], v[72:73]
	v_pk_mul_f32 v[66:67], v[26:27], v[66:67]
	v_cvt_pk_bf16_f32 v48, v60, v61
	v_cvt_pk_bf16_f32 v49, v62, v63
	v_cvt_pk_bf16_f32 v50, v52, v53
	v_cvt_pk_bf16_f32 v51, v54, v55
	v_cvt_pk_bf16_f32 v62, v64, v65
	v_pk_fma_f32 v[64:65], v[118:119], s[10:11], v[100:101] op_sel_hi:[1,0,0]
	v_cvt_pk_bf16_f32 v52, v56, v57
	v_cvt_pk_bf16_f32 v53, v58, v59
	v_cvt_pk_bf16_f32 v54, v124, v125
	v_cvt_pk_bf16_f32 v55, v122, v123
	v_cvt_pk_bf16_f32 v56, v76, v77
	v_cvt_pk_bf16_f32 v57, v78, v79
	v_cvt_pk_bf16_f32 v58, v68, v69
	v_cvt_pk_bf16_f32 v59, v70, v71
	v_cvt_pk_bf16_f32 v60, v72, v73
	v_cvt_pk_bf16_f32 v61, v74, v75
	v_cvt_pk_bf16_f32 v63, v66, v67
	global_store_dwordx4 v[114:115], v[48:51], off
	global_store_dwordx4 v[114:115], v[52:55], off offset:1024
	global_store_dwordx4 v[116:117], v[56:59], off
	global_store_dwordx4 v[116:117], v[60:63], off offset:1024
	v_mul_f32_e32 v48, 0x4b800000, v65
	v_cmp_gt_f32_e64 s[0:1], s13, v65
	v_mul_f32_e32 v49, 0x4b800000, v64
	v_cmp_gt_f32_e32 vcc, s13, v64
	v_cndmask_b32_e64 v48, v65, v48, s[0:1]
	v_rsq_f32_e32 v48, v48
	v_cndmask_b32_e32 v49, v64, v49, vcc
	v_rsq_f32_e32 v49, v49
	v_mul_f32_e32 v50, 0x45800000, v48
	v_cndmask_b32_e64 v48, v48, v50, s[0:1]
	v_mul_f32_e32 v51, 0x45800000, v49
	v_cndmask_b32_e32 v50, v49, v51, vcc
	v_pk_mul_f32 v[44:45], v[44:45], v[48:49] op_sel_hi:[1,0]
	v_pk_mul_f32 v[46:47], v[46:47], v[48:49] op_sel_hi:[1,0]
	v_pk_mul_f32 v[36:37], v[36:37], v[48:49] op_sel_hi:[1,0]
	v_pk_mul_f32 v[38:39], v[38:39], v[48:49] op_sel_hi:[1,0]
	v_pk_mul_f32 v[40:41], v[40:41], v[48:49] op_sel_hi:[1,0]
	v_pk_mul_f32 v[42:43], v[42:43], v[48:49] op_sel_hi:[1,0]
	v_pk_mul_f32 v[32:33], v[32:33], v[48:49] op_sel_hi:[1,0]
	v_pk_mul_f32 v[34:35], v[34:35], v[48:49] op_sel_hi:[1,0]
	v_pk_mul_f32 v[48:49], v[92:93], v[50:51] op_sel_hi:[1,0]
	v_pk_mul_f32 v[52:53], v[94:95], v[50:51] op_sel_hi:[1,0]
	v_pk_mul_f32 v[54:55], v[84:85], v[50:51] op_sel_hi:[1,0]
	v_pk_mul_f32 v[56:57], v[86:87], v[50:51] op_sel_hi:[1,0]
	v_pk_mul_f32 v[58:59], v[88:89], v[50:51] op_sel_hi:[1,0]
	v_pk_mul_f32 v[60:61], v[90:91], v[50:51] op_sel_hi:[1,0]
	v_pk_mul_f32 v[62:63], v[80:81], v[50:51] op_sel_hi:[1,0]
	v_pk_mul_f32 v[50:51], v[82:83], v[50:51] op_sel_hi:[1,0]
	v_pk_mul_f32 v[46:47], v[22:23], v[46:47]
	v_pk_mul_f32 v[44:45], v[20:21], v[44:45]
	v_pk_mul_f32 v[38:39], v[18:19], v[38:39]
	v_pk_mul_f32 v[36:37], v[16:17], v[36:37]
	v_pk_mul_f32 v[42:43], v[30:31], v[42:43]
	v_pk_mul_f32 v[40:41], v[28:29], v[40:41]
	v_pk_mul_f32 v[64:65], v[26:27], v[34:35]
	v_pk_mul_f32 v[66:67], v[24:25], v[32:33]
	v_pk_mul_f32 v[52:53], v[22:23], v[52:53]
	v_pk_mul_f32 v[48:49], v[20:21], v[48:49]
	v_pk_mul_f32 v[56:57], v[18:19], v[56:57]
	v_pk_mul_f32 v[54:55], v[16:17], v[54:55]
	v_pk_mul_f32 v[60:61], v[30:31], v[60:61]
	v_pk_mul_f32 v[58:59], v[28:29], v[58:59]
	v_pk_mul_f32 v[50:51], v[26:27], v[50:51]
	v_pk_mul_f32 v[62:63], v[24:25], v[62:63]
	v_cvt_pk_bf16_f32 v32, v44, v45
	v_cvt_pk_bf16_f32 v33, v46, v47
	v_cvt_pk_bf16_f32 v34, v36, v37
	v_cvt_pk_bf16_f32 v35, v38, v39
	v_cvt_pk_bf16_f32 v36, v40, v41
	v_cvt_pk_bf16_f32 v37, v42, v43
	v_cvt_pk_bf16_f32 v38, v66, v67
	v_cvt_pk_bf16_f32 v39, v64, v65
	v_cvt_pk_bf16_f32 v40, v48, v49
	v_cvt_pk_bf16_f32 v41, v52, v53
	v_cvt_pk_bf16_f32 v42, v54, v55
	v_cvt_pk_bf16_f32 v43, v56, v57
	v_cvt_pk_bf16_f32 v44, v58, v59
	v_cvt_pk_bf16_f32 v45, v60, v61
	v_cvt_pk_bf16_f32 v46, v62, v63
	v_cvt_pk_bf16_f32 v47, v50, v51
	global_store_dwordx4 v[104:105], v[32:35], off
	global_store_dwordx4 v[104:105], v[36:39], off offset:1024
	global_store_dwordx4 v[102:103], v[40:43], off
	global_store_dwordx4 v[102:103], v[44:47], off offset:1024
	v_readfirstlane_b32 s98, v140
	s_lshr_b32 s99, s98, 8
	s_add_i32 s99, s99, 1
	s_lshl_b32 s99, s99, 13
	s_and_b32 s16, s98, 0xff
	s_lshr_b32 s100, s16, 3
	s_lshl_b32 s100, s100, 3
	s_and_b32 s101, s2, 7
	s_or_b32 s100, s100, s101
	s_lshl_b32 s100, s100, 3
	s_and_b32 s16, s16, 7
	s_or_b32 s16, s16, s100
	s_add_i32 s16, s16, s99
	s_cmp_gt_u32 s98, 0x2ff
	s_cbranch_scc0 .LBB0_76
.LBB0_77:
	s_add_i32 s16, s29, 0x8000
	s_cmp_gt_i32 s16, 0x81ff
	s_cbranch_scc1 .LBB0_80
	v_mbcnt_hi_u32_b32 v32, -1, v221
	v_and_b32_e32 v33, 64, v32
	v_add_u32_e32 v33, 64, v33
	v_xor_b32_e32 v34, 1, v32
	v_cmp_lt_i32_e32 vcc, v34, v33
	v_xor_b32_e32 v35, 2, v32
	v_xor_b32_e32 v36, 4, v32
	v_cndmask_b32_e32 v34, v32, v34, vcc
	v_cmp_lt_i32_e32 vcc, v35, v33
	v_xor_b32_e32 v37, 8, v32
	v_xor_b32_e32 v38, 16, v32
	v_cndmask_b32_e32 v35, v32, v35, vcc
	v_cmp_lt_i32_e32 vcc, v36, v33
	v_xor_b32_e32 v39, 32, v32
	s_ashr_i32 s17, s16, 31
	v_cndmask_b32_e32 v36, v32, v36, vcc
	v_cmp_lt_i32_e32 vcc, v37, v33
	s_lshl_b64 s[0:1], s[16:17], 11
	s_add_u32 s0, s20, s0
	v_cndmask_b32_e32 v37, v32, v37, vcc
	v_cmp_lt_i32_e32 vcc, v38, v33
	s_addc_u32 s1, s21, s1
	s_ashr_i32 s93, s92, 31
	v_cndmask_b32_e32 v38, v32, v38, vcc
	v_cmp_lt_i32_e32 vcc, v39, v33
	v_mov_b32_e32 v33, 0
	v_lshlrev_b32_e32 v34, 2, v34
	v_cndmask_b32_e32 v32, v32, v39, vcc
	v_lshlrev_b32_e32 v39, 2, v32
	v_lshlrev_b32_e32 v32, 4, v97
	v_lshl_add_u64 v[32:33], s[0:1], 0, v[32:33]
	s_mov_b64 s[0:1], 0x3600000
	v_lshlrev_b32_e32 v35, 2, v35
	v_lshlrev_b32_e32 v36, 2, v36
	v_lshlrev_b32_e32 v37, 2, v37
	v_lshlrev_b32_e32 v38, 2, v38
	v_lshl_add_u64 v[32:33], v[32:33], 0, s[0:1]
	s_lshl_b64 s[0:1], s[92:93], 11
	v_lshlrev_b32_e32 v40, 2, v106
	v_mov_b32_e32 v41, 0x358637bd
	s_mov_b32 s10, 0x800000
